# P4 epilogue: row-statistic atomics deferred past the next batch's residual loads so counted waits no longer sit behind them
# speedup vs baseline: 1.0022x; 1.0022x over previous
; __device__ __forceinline__ unsigned cvt_pk_bf16(float lo, float hi) { unsigned r; asm volatile("v_cvt_pk_bf16_f32 %0, %1, %2" : "=v"(r) : "v"(lo), "v"(hi)); return r; }
;     __device__ __forceinline__ void operator()(const f32x4 (&acc)[2][2][4][2], const Unit& u, int wr, int wc, int fr, int fq) const {
;     ...
;                 for (int ml = 0; ml < 2; ++ml) { const int m = 2 * mh + ml; const int row = row0 + ai * HALF + m * 16; float s = 0.f;
; #pragma unroll
;                     for (int bj = 0; bj < 2; ++bj) { const size_t off = (size_t)row * 1024 + col0 + bj * HALF;
;                         const f32x4 v0 = bv[ml][bj][0] + acc[ai][bj][m][0], v1 = bv[ml][bj][1] + acc[ai][bj][m][1];
;                         *(f32x4*)(out + off) = v0; *(f32x4*)(out + off + 4) = v1;
;                         u32x4 w; w.x = cvt_pk_bf16(v0[0], v0[1]); w.y = cvt_pk_bf16(v0[2], v0[3]); w.z = cvt_pk_bf16(v1[0], v1[1]); w.w = cvt_pk_bf16(v1[2], v1[3]);
;                         if (xb) *(u32x4*)(xb + off) = w;
;                         s += (v0[0] * v0[0] + v0[1] * v0[1]) + (v0[2] * v0[2] + v0[3] * v0[3]) + (v1[0] * v1[0] + v1[1] * v1[1]) + (v1[2] * v1[2] + v1[3] * v1[3]); }
;                     s += __shfl_xor(s, 16); s += __shfl_xor(s, 32);
;                     if (fq == 0) atomicAdd(rowss_next + row, s); }
.LBB0_544:
	v_mul_f32_e32 v125, v125, v125
	v_mul_f32_e32 v117, v117, v117
	v_fmac_f32_e32 v125, v124, v124
	v_mul_f32_e32 v124, v127, v127
	v_fmac_f32_e32 v117, v116, v116
	v_mul_f32_e32 v116, v119, v119
	v_fmac_f32_e32 v124, v126, v126
	v_mul_f32_e32 v121, v121, v121
	v_fmac_f32_e32 v116, v118, v118
	v_mul_f32_e32 v113, v113, v113
	v_add_f32_e32 v124, v125, v124
	v_fmac_f32_e32 v121, v120, v120
	v_add_f32_e32 v116, v117, v116
	v_fmac_f32_e32 v113, v112, v112
	v_add_f32_e32 v120, v124, v121
	v_mul_f32_e32 v121, v123, v123
	v_add_f32_e32 v112, v116, v113
	v_mul_f32_e32 v113, v115, v115
	v_fmac_f32_e32 v121, v122, v122
	v_fmac_f32_e32 v113, v114, v114
	v_add_f32_e32 v120, v121, v120
	v_add_f32_e32 v112, v113, v112
	v_add_f32_e32 v112, v120, v112
	ds_bpermute_b32 v113, v241, v112
	v_lshl_add_u64 v[124:125], v[172:173], 2, s[20:21]
	s_waitcnt lgkmcnt(0)
	v_add_f32_e32 v112, v112, v113
	ds_bpermute_b32 v113, v242, v112
	s_waitcnt lgkmcnt(0)
	v_add_f32_e32 v243, v112, v113
	s_waitcnt lgkmcnt(0)
	v_lshlrev_b64 v[112:113], 10, v[174:175]
	v_lshl_add_u64 v[118:119], v[112:113], 0, v[168:169]
	v_pk_add_f32 v[110:111], v[110:111], v[142:143]
	v_pk_add_f32 v[108:109], v[108:109], v[140:141]
	v_pk_add_f32 v[106:107], v[106:107], v[138:139]
	v_pk_add_f32 v[104:105], v[104:105], v[136:137]
	v_lshl_add_u64 v[116:117], v[118:119], 2, s[10:11]
	s_and_b64 vcc, exec, s[6:7]
	v_lshl_add_u64 v[118:119], v[118:119], 1, s[18:19]
	global_store_dwordx4 v[116:117], v[108:111], off
	global_store_dwordx4 v[116:117], v[104:107], off offset:16
	v_cvt_pk_bf16_f32 v112, v108, v109
	v_cvt_pk_bf16_f32 v113, v110, v111
	v_cvt_pk_bf16_f32 v114, v104, v105
	v_cvt_pk_bf16_f32 v115, v106, v107
	s_cbranch_vccnz .LBB0_548
	global_store_dwordx4 v[118:119], v[112:115], off

;     __device__ __forceinline__ void operator()(const f32x4 (&acc)[2][2][4][2], const Unit& u, int wr, int wc, int fr, int fq) const {
;     ...
;                 f32x4 bv[2][2][2];
; #pragma unroll
;                 for (int ml = 0; ml < 2; ++ml)
; #pragma unroll
;                     for (int bj = 0; bj < 2; ++bj) { const size_t off = (size_t)(row0 + ai * HALF + (2 * mh + ml) * 16) * 1024 + col0 + bj * HALF;
;                         bv[ml][bj][0] = *(const f32x4*)(base + off); bv[ml][bj][1] = *(const f32x4*)(base + off + 4); }
;     ...
;                         s += (v0[0] * v0[0] + v0[1] * v0[1]) + (v0[2] * v0[2] + v0[3] * v0[3]) + (v1[0] * v1[0] + v1[1] * v1[1]) + (v1[2] * v1[2] + v1[3] * v1[3]); }
;                     s += __shfl_xor(s, 16); s += __shfl_xor(s, 32);
;                     if (fq == 0) atomicAdd(rowss_next + row, s); }
.LBB0_550:
	v_mul_f32_e32 v109, v109, v109
	v_mul_f32_e32 v101, v101, v101
	v_fmac_f32_e32 v109, v108, v108
	v_mul_f32_e32 v108, v111, v111
	v_fmac_f32_e32 v101, v100, v100
	v_mul_f32_e32 v100, v103, v103
	v_fmac_f32_e32 v108, v110, v110
	v_mul_f32_e32 v105, v105, v105
	v_fmac_f32_e32 v100, v102, v102
	v_mul_f32_e32 v97, v97, v97
	v_add_f32_e32 v108, v109, v108
	v_fmac_f32_e32 v105, v104, v104
	v_add_f32_e32 v100, v101, v100
	v_fmac_f32_e32 v97, v96, v96
	v_add_f32_e32 v104, v108, v105
	v_mul_f32_e32 v105, v107, v107
	v_add_f32_e32 v96, v100, v97
	v_mul_f32_e32 v97, v99, v99
	v_fmac_f32_e32 v105, v106, v106
	v_fmac_f32_e32 v97, v98, v98
	v_add_f32_e32 v104, v105, v104
	v_add_f32_e32 v96, v97, v96
	v_add_f32_e32 v96, v104, v96
	ds_bpermute_b32 v97, v241, v96
	s_waitcnt lgkmcnt(0)
	v_add_f32_e32 v96, v96, v97
	ds_bpermute_b32 v97, v242, v96
	s_waitcnt lgkmcnt(0)
	v_add_f32_e32 v246, v96, v97
	v_or_b32_e32 v132, 32, v172
	v_ashrrev_i32_e32 v133, 31, v132
	s_waitcnt lgkmcnt(0)
	v_lshlrev_b64 v[96:97], 12, v[132:133]
	v_or_b32_e32 v126, 48, v172
	v_lshl_add_u64 v[96:97], v[170:171], 0, v[96:97]
	v_ashrrev_i32_e32 v127, 31, v126
	global_load_dwordx4 v[120:123], v[96:97], off offset:16
	global_load_dwordx4 v[128:131], v[96:97], off
	global_load_dwordx4 v[112:115], v[96:97], off offset:528
	global_load_dwordx4 v[116:119], v[96:97], off offset:512
	v_lshlrev_b64 v[96:97], 12, v[126:127]
	v_lshl_add_u64 v[100:101], v[170:171], 0, v[96:97]
	global_load_dwordx4 v[104:107], v[100:101], off offset:16
	global_load_dwordx4 v[108:111], v[100:101], off
	global_load_dwordx4 v[96:99], v[100:101], off offset:528
	s_nop 0
	global_load_dwordx4 v[100:103], v[100:101], off offset:512
	s_and_saveexec_b64 s[100:101], s[4:5]
	global_atomic_add_f32 v[124:125], v243, off
	global_atomic_add_f32 v[124:125], v246, off offset:64
	s_or_b64 exec, exec, s[100:101]
	v_lshlrev_b64 v[132:133], 10, v[132:133]
	v_lshl_add_u64 v[132:133], v[132:133], 0, v[168:169]
	s_and_b64 vcc, exec, s[6:7]
	s_waitcnt vmcnt(7)
	v_pk_add_f32 v[90:91], v[90:91], v[122:123]
	s_waitcnt vmcnt(6)
	v_pk_add_f32 v[94:95], v[94:95], v[130:131]
	v_pk_add_f32 v[92:93], v[92:93], v[128:129]
	v_pk_add_f32 v[88:89], v[88:89], v[120:121]
	v_lshl_add_u64 v[128:129], v[132:133], 2, s[10:11]
	v_lshl_add_u64 v[130:131], v[132:133], 1, s[18:19]
	global_store_dwordx4 v[128:129], v[92:95], off
	global_store_dwordx4 v[128:129], v[88:91], off offset:16
	v_cvt_pk_bf16_f32 v120, v92, v93
	v_cvt_pk_bf16_f32 v121, v94, v95
	v_cvt_pk_bf16_f32 v122, v88, v89
	v_cvt_pk_bf16_f32 v123, v90, v91
	s_cbranch_vccnz .LBB0_554
	global_store_dwordx4 v[130:131], v[120:123], off

; __device__ __forceinline__ unsigned cvt_pk_bf16(float lo, float hi) { unsigned r; asm volatile("v_cvt_pk_bf16_f32 %0, %1, %2" : "=v"(r) : "v"(lo), "v"(hi)); return r; }
;     __device__ __forceinline__ void operator()(const f32x4 (&acc)[2][2][4][2], const Unit& u, int wr, int wc, int fr, int fq) const {
;     ...
;                 for (int ml = 0; ml < 2; ++ml) { const int m = 2 * mh + ml; const int row = row0 + ai * HALF + m * 16; float s = 0.f;
; #pragma unroll
;                     for (int bj = 0; bj < 2; ++bj) { const size_t off = (size_t)row * 1024 + col0 + bj * HALF;
;                         const f32x4 v0 = bv[ml][bj][0] + acc[ai][bj][m][0], v1 = bv[ml][bj][1] + acc[ai][bj][m][1];
;                         *(f32x4*)(out + off) = v0; *(f32x4*)(out + off + 4) = v1;
;                         u32x4 w; w.x = cvt_pk_bf16(v0[0], v0[1]); w.y = cvt_pk_bf16(v0[2], v0[3]); w.z = cvt_pk_bf16(v1[0], v1[1]); w.w = cvt_pk_bf16(v1[2], v1[3]);
;                         if (xb) *(u32x4*)(xb + off) = w;
;                         s += (v0[0] * v0[0] + v0[1] * v0[1]) + (v0[2] * v0[2] + v0[3] * v0[3]) + (v1[0] * v1[0] + v1[1] * v1[1]) + (v1[2] * v1[2] + v1[3] * v1[3]); }
;                     s += __shfl_xor(s, 16); s += __shfl_xor(s, 32);
;                     if (fq == 0) atomicAdd(rowss_next + row, s); }
.LBB0_556:
	v_mul_f32_e32 v93, v93, v93
	v_mul_f32_e32 v85, v85, v85
	v_fmac_f32_e32 v93, v92, v92
	v_mul_f32_e32 v92, v95, v95
	v_fmac_f32_e32 v85, v84, v84
	v_mul_f32_e32 v84, v87, v87
	v_fmac_f32_e32 v92, v94, v94
	v_mul_f32_e32 v89, v89, v89
	v_fmac_f32_e32 v84, v86, v86
	v_mul_f32_e32 v81, v81, v81
	v_add_f32_e32 v92, v93, v92
	v_fmac_f32_e32 v89, v88, v88
	v_add_f32_e32 v84, v85, v84
	v_fmac_f32_e32 v81, v80, v80
	v_add_f32_e32 v88, v92, v89
	v_mul_f32_e32 v89, v91, v91
	v_add_f32_e32 v80, v84, v81
	v_mul_f32_e32 v81, v83, v83
	v_fmac_f32_e32 v89, v90, v90
	v_fmac_f32_e32 v81, v82, v82
	v_add_f32_e32 v88, v89, v88
	v_add_f32_e32 v80, v81, v80
	v_add_f32_e32 v80, v88, v80
	ds_bpermute_b32 v81, v241, v80
	s_waitcnt lgkmcnt(0)
	v_add_f32_e32 v80, v80, v81
	ds_bpermute_b32 v81, v242, v80
	s_waitcnt lgkmcnt(0)
	v_add_f32_e32 v243, v80, v81
	s_waitcnt lgkmcnt(0)
	v_lshlrev_b64 v[80:81], 10, v[126:127]
	v_lshl_add_u64 v[86:87], v[80:81], 0, v[168:169]
	s_waitcnt vmcnt(6)
	v_pk_add_f32 v[78:79], v[78:79], v[110:111]
	v_pk_add_f32 v[76:77], v[76:77], v[108:109]
	v_pk_add_f32 v[74:75], v[74:75], v[106:107]
	v_pk_add_f32 v[72:73], v[72:73], v[104:105]
	v_lshl_add_u64 v[84:85], v[86:87], 2, s[10:11]
	s_and_b64 vcc, exec, s[6:7]
	v_lshl_add_u64 v[86:87], v[86:87], 1, s[18:19]
	global_store_dwordx4 v[84:85], v[76:79], off
	global_store_dwordx4 v[84:85], v[72:75], off offset:16
	v_cvt_pk_bf16_f32 v80, v76, v77
	v_cvt_pk_bf16_f32 v81, v78, v79
	v_cvt_pk_bf16_f32 v82, v72, v73
	v_cvt_pk_bf16_f32 v83, v74, v75
	s_cbranch_vccnz .LBB0_560
	global_store_dwordx4 v[86:87], v[80:83], off

;     __device__ __forceinline__ void operator()(const f32x4 (&acc)[2][2][4][2], const Unit& u, int wr, int wc, int fr, int fq) const {
;     ...
;                 f32x4 bv[2][2][2];
; #pragma unroll
;                 for (int ml = 0; ml < 2; ++ml)
; #pragma unroll
;                     for (int bj = 0; bj < 2; ++bj) { const size_t off = (size_t)(row0 + ai * HALF + (2 * mh + ml) * 16) * 1024 + col0 + bj * HALF;
;                         bv[ml][bj][0] = *(const f32x4*)(base + off); bv[ml][bj][1] = *(const f32x4*)(base + off + 4); }
;     ...
;                         s += (v0[0] * v0[0] + v0[1] * v0[1]) + (v0[2] * v0[2] + v0[3] * v0[3]) + (v1[0] * v1[0] + v1[1] * v1[1]) + (v1[2] * v1[2] + v1[3] * v1[3]); }
;                     s += __shfl_xor(s, 16); s += __shfl_xor(s, 32);
;                     if (fq == 0) atomicAdd(rowss_next + row, s); }
.LBB0_562:
	v_mul_f32_e32 v77, v77, v77
	v_mul_f32_e32 v69, v69, v69
	v_fmac_f32_e32 v77, v76, v76
	v_mul_f32_e32 v76, v79, v79
	v_fmac_f32_e32 v69, v68, v68
	v_mul_f32_e32 v68, v71, v71
	v_fmac_f32_e32 v76, v78, v78
	v_mul_f32_e32 v73, v73, v73
	v_fmac_f32_e32 v68, v70, v70
	v_mul_f32_e32 v65, v65, v65
	v_add_f32_e32 v76, v77, v76
	v_fmac_f32_e32 v73, v72, v72
	v_add_f32_e32 v68, v69, v68
	v_fmac_f32_e32 v65, v64, v64
	v_add_f32_e32 v72, v76, v73
	v_mul_f32_e32 v73, v75, v75
	v_add_f32_e32 v64, v68, v65
	v_mul_f32_e32 v65, v67, v67
	v_fmac_f32_e32 v73, v74, v74
	v_fmac_f32_e32 v65, v66, v66
	v_add_f32_e32 v72, v73, v72
	v_add_f32_e32 v64, v65, v64
	v_add_f32_e32 v64, v72, v64
	ds_bpermute_b32 v65, v241, v64
	s_waitcnt lgkmcnt(0)
	v_add_f32_e32 v64, v64, v65
	ds_bpermute_b32 v65, v242, v64
	s_waitcnt lgkmcnt(0)
	v_add_f32_e32 v246, v64, v65
	v_add_u32_e32 v98, 0x80, v172
	v_ashrrev_i32_e32 v99, 31, v98
	s_waitcnt lgkmcnt(0)
	v_lshlrev_b64 v[64:65], 12, v[98:99]
	v_add_u32_e32 v92, 0x90, v172
	v_lshl_add_u64 v[64:65], v[170:171], 0, v[64:65]
	v_ashrrev_i32_e32 v93, 31, v92
	global_load_dwordx4 v[88:91], v[64:65], off offset:16
	global_load_dwordx4 v[94:97], v[64:65], off
	global_load_dwordx4 v[80:83], v[64:65], off offset:528
	global_load_dwordx4 v[84:87], v[64:65], off offset:512
	v_lshlrev_b64 v[64:65], 12, v[92:93]
	v_lshl_add_u64 v[68:69], v[170:171], 0, v[64:65]
	global_load_dwordx4 v[72:75], v[68:69], off offset:16
	global_load_dwordx4 v[76:79], v[68:69], off
	global_load_dwordx4 v[64:67], v[68:69], off offset:528
	s_nop 0
	global_load_dwordx4 v[68:71], v[68:69], off offset:512
	s_and_saveexec_b64 s[100:101], s[4:5]
	global_atomic_add_f32 v[124:125], v243, off offset:128
	global_atomic_add_f32 v[124:125], v246, off offset:192
	s_or_b64 exec, exec, s[100:101]
	v_lshlrev_b64 v[98:99], 10, v[98:99]
	v_lshl_add_u64 v[98:99], v[98:99], 0, v[168:169]
	s_and_b64 vcc, exec, s[6:7]
	s_waitcnt vmcnt(7)
	v_pk_add_f32 v[58:59], v[58:59], v[90:91]
	s_waitcnt vmcnt(6)
	v_pk_add_f32 v[62:63], v[62:63], v[96:97]
	v_pk_add_f32 v[60:61], v[60:61], v[94:95]
	v_pk_add_f32 v[56:57], v[56:57], v[88:89]
	v_lshl_add_u64 v[94:95], v[98:99], 2, s[10:11]
	v_lshl_add_u64 v[96:97], v[98:99], 1, s[18:19]
	global_store_dwordx4 v[94:95], v[60:63], off
	global_store_dwordx4 v[94:95], v[56:59], off offset:16
	v_cvt_pk_bf16_f32 v88, v60, v61
	v_cvt_pk_bf16_f32 v89, v62, v63
	v_cvt_pk_bf16_f32 v90, v56, v57
	v_cvt_pk_bf16_f32 v91, v58, v59
	s_cbranch_vccnz .LBB0_566
	global_store_dwordx4 v[96:97], v[88:91], off

; __device__ __forceinline__ unsigned cvt_pk_bf16(float lo, float hi) { unsigned r; asm volatile("v_cvt_pk_bf16_f32 %0, %1, %2" : "=v"(r) : "v"(lo), "v"(hi)); return r; }
;     __device__ __forceinline__ void operator()(const f32x4 (&acc)[2][2][4][2], const Unit& u, int wr, int wc, int fr, int fq) const {
;     ...
;                 for (int ml = 0; ml < 2; ++ml) { const int m = 2 * mh + ml; const int row = row0 + ai * HALF + m * 16; float s = 0.f;
; #pragma unroll
;                     for (int bj = 0; bj < 2; ++bj) { const size_t off = (size_t)row * 1024 + col0 + bj * HALF;
;                         const f32x4 v0 = bv[ml][bj][0] + acc[ai][bj][m][0], v1 = bv[ml][bj][1] + acc[ai][bj][m][1];
;                         *(f32x4*)(out + off) = v0; *(f32x4*)(out + off + 4) = v1;
;                         u32x4 w; w.x = cvt_pk_bf16(v0[0], v0[1]); w.y = cvt_pk_bf16(v0[2], v0[3]); w.z = cvt_pk_bf16(v1[0], v1[1]); w.w = cvt_pk_bf16(v1[2], v1[3]);
;                         if (xb) *(u32x4*)(xb + off) = w;
;                         s += (v0[0] * v0[0] + v0[1] * v0[1]) + (v0[2] * v0[2] + v0[3] * v0[3]) + (v1[0] * v1[0] + v1[1] * v1[1]) + (v1[2] * v1[2] + v1[3] * v1[3]); }
;                     s += __shfl_xor(s, 16); s += __shfl_xor(s, 32);
;                     if (fq == 0) atomicAdd(rowss_next + row, s); }
.LBB0_568:
	v_mul_f32_e32 v61, v61, v61
	v_mul_f32_e32 v53, v53, v53
	v_fmac_f32_e32 v61, v60, v60
	v_mul_f32_e32 v60, v63, v63
	v_fmac_f32_e32 v53, v52, v52
	v_mul_f32_e32 v52, v55, v55
	v_fmac_f32_e32 v60, v62, v62
	v_mul_f32_e32 v57, v57, v57
	v_fmac_f32_e32 v52, v54, v54
	v_mul_f32_e32 v49, v49, v49
	v_add_f32_e32 v60, v61, v60
	v_fmac_f32_e32 v57, v56, v56
	v_add_f32_e32 v52, v53, v52
	v_fmac_f32_e32 v49, v48, v48
	v_add_f32_e32 v56, v60, v57
	v_mul_f32_e32 v57, v59, v59
	v_add_f32_e32 v48, v52, v49
	v_mul_f32_e32 v49, v51, v51
	v_fmac_f32_e32 v57, v58, v58
	v_fmac_f32_e32 v49, v50, v50
	v_add_f32_e32 v56, v57, v56
	v_add_f32_e32 v48, v49, v48
	v_add_f32_e32 v48, v56, v48
	ds_bpermute_b32 v49, v241, v48
	s_waitcnt lgkmcnt(0)
	v_add_f32_e32 v48, v48, v49
	ds_bpermute_b32 v49, v242, v48
	s_waitcnt lgkmcnt(0)
	v_add_f32_e32 v243, v48, v49
	s_waitcnt lgkmcnt(0)
	v_lshlrev_b64 v[48:49], 10, v[92:93]
	v_lshl_add_u64 v[54:55], v[48:49], 0, v[168:169]
	s_waitcnt vmcnt(6)
	v_pk_add_f32 v[46:47], v[46:47], v[78:79]
	v_pk_add_f32 v[44:45], v[44:45], v[76:77]
	v_pk_add_f32 v[42:43], v[42:43], v[74:75]
	v_pk_add_f32 v[40:41], v[40:41], v[72:73]
	v_lshl_add_u64 v[52:53], v[54:55], 2, s[10:11]
	s_and_b64 vcc, exec, s[6:7]
	v_lshl_add_u64 v[54:55], v[54:55], 1, s[18:19]
	global_store_dwordx4 v[52:53], v[44:47], off
	global_store_dwordx4 v[52:53], v[40:43], off offset:16
	v_cvt_pk_bf16_f32 v48, v44, v45
	v_cvt_pk_bf16_f32 v49, v46, v47
	v_cvt_pk_bf16_f32 v50, v40, v41
	v_cvt_pk_bf16_f32 v51, v42, v43
	s_cbranch_vccnz .LBB0_572
	global_store_dwordx4 v[54:55], v[48:51], off

; __device__ __forceinline__ unsigned cvt_pk_bf16(float lo, float hi) { unsigned r; asm volatile("v_cvt_pk_bf16_f32 %0, %1, %2" : "=v"(r) : "v"(lo), "v"(hi)); return r; }
;     __device__ __forceinline__ void operator()(const f32x4 (&acc)[2][2][4][2], const Unit& u, int wr, int wc, int fr, int fq) const {
;     ...
;                 f32x4 bv[2][2][2];
; #pragma unroll
;                 for (int ml = 0; ml < 2; ++ml)
; #pragma unroll
;                     for (int bj = 0; bj < 2; ++bj) { const size_t off = (size_t)(row0 + ai * HALF + (2 * mh + ml) * 16) * 1024 + col0 + bj * HALF;
;                         bv[ml][bj][0] = *(const f32x4*)(base + off); bv[ml][bj][1] = *(const f32x4*)(base + off + 4); }
;                 asm volatile("" ::: "memory");
; #pragma unroll
;                 for (int ml = 0; ml < 2; ++ml) { const int m = 2 * mh + ml; const int row = row0 + ai * HALF + m * 16; float s = 0.f;
; #pragma unroll
;                     for (int bj = 0; bj < 2; ++bj) { const size_t off = (size_t)row * 1024 + col0 + bj * HALF;
;                         const f32x4 v0 = bv[ml][bj][0] + acc[ai][bj][m][0], v1 = bv[ml][bj][1] + acc[ai][bj][m][1];
;                         *(f32x4*)(out + off) = v0; *(f32x4*)(out + off + 4) = v1;
;                         u32x4 w; w.x = cvt_pk_bf16(v0[0], v0[1]); w.y = cvt_pk_bf16(v0[2], v0[3]); w.z = cvt_pk_bf16(v1[0], v1[1]); w.w = cvt_pk_bf16(v1[2], v1[3]);
;                         if (xb) *(u32x4*)(xb + off) = w;
;                         s += (v0[0] * v0[0] + v0[1] * v0[1]) + (v0[2] * v0[2] + v0[3] * v0[3]) + (v1[0] * v1[0] + v1[1] * v1[1]) + (v1[2] * v1[2] + v1[3] * v1[3]); }
;                     s += __shfl_xor(s, 16); s += __shfl_xor(s, 32);
;                     if (fq == 0) atomicAdd(rowss_next + row, s); }
.LBB0_574:
	v_mul_f32_e32 v45, v45, v45
	v_mul_f32_e32 v37, v37, v37
	v_fmac_f32_e32 v45, v44, v44
	v_mul_f32_e32 v44, v47, v47
	v_fmac_f32_e32 v37, v36, v36
	v_mul_f32_e32 v36, v39, v39
	v_fmac_f32_e32 v44, v46, v46
	v_mul_f32_e32 v41, v41, v41
	v_fmac_f32_e32 v36, v38, v38
	v_mul_f32_e32 v33, v33, v33
	v_add_f32_e32 v44, v45, v44
	v_fmac_f32_e32 v41, v40, v40
	v_add_f32_e32 v36, v37, v36
	v_fmac_f32_e32 v33, v32, v32
	v_add_f32_e32 v40, v44, v41
	v_mul_f32_e32 v41, v43, v43
	v_add_f32_e32 v32, v36, v33
	v_mul_f32_e32 v33, v35, v35
	v_fmac_f32_e32 v41, v42, v42
	v_fmac_f32_e32 v33, v34, v34
	v_add_f32_e32 v40, v41, v40
	v_add_f32_e32 v32, v33, v32
	v_add_f32_e32 v32, v40, v32
	ds_bpermute_b32 v33, v241, v32
	s_waitcnt lgkmcnt(0)
	v_add_f32_e32 v32, v32, v33
	ds_bpermute_b32 v33, v242, v32
	s_waitcnt lgkmcnt(0)
	v_add_f32_e32 v246, v32, v33
	v_add_u32_e32 v66, 0xa0, v172
	v_ashrrev_i32_e32 v67, 31, v66
	s_waitcnt lgkmcnt(0)
	v_lshlrev_b64 v[32:33], 12, v[66:67]
	v_add_u32_e32 v60, 0xb0, v172
	v_lshl_add_u64 v[32:33], v[170:171], 0, v[32:33]
	v_ashrrev_i32_e32 v61, 31, v60
	global_load_dwordx4 v[56:59], v[32:33], off offset:16
	global_load_dwordx4 v[62:65], v[32:33], off
	global_load_dwordx4 v[48:51], v[32:33], off offset:528
	global_load_dwordx4 v[52:55], v[32:33], off offset:512
	v_lshlrev_b64 v[32:33], 12, v[60:61]
	v_lshl_add_u64 v[36:37], v[170:171], 0, v[32:33]
	global_load_dwordx4 v[40:43], v[36:37], off offset:16
	global_load_dwordx4 v[44:47], v[36:37], off
	global_load_dwordx4 v[32:35], v[36:37], off offset:528
	s_nop 0
	global_load_dwordx4 v[36:39], v[36:37], off offset:512
	s_and_saveexec_b64 s[100:101], s[4:5]
	global_atomic_add_f32 v[124:125], v243, off offset:512
	global_atomic_add_f32 v[124:125], v246, off offset:576
	s_or_b64 exec, exec, s[100:101]
	v_lshlrev_b64 v[66:67], 10, v[66:67]
	v_lshl_add_u64 v[66:67], v[66:67], 0, v[168:169]
	s_and_b64 vcc, exec, s[6:7]
	s_waitcnt vmcnt(7)
	v_pk_add_f32 v[26:27], v[26:27], v[58:59]
	s_waitcnt vmcnt(6)
	v_pk_add_f32 v[30:31], v[30:31], v[64:65]
	v_pk_add_f32 v[28:29], v[28:29], v[62:63]
	v_pk_add_f32 v[24:25], v[24:25], v[56:57]
	v_lshl_add_u64 v[62:63], v[66:67], 2, s[10:11]
	v_lshl_add_u64 v[64:65], v[66:67], 1, s[18:19]
	global_store_dwordx4 v[62:63], v[28:31], off
	global_store_dwordx4 v[62:63], v[24:27], off offset:16
	v_cvt_pk_bf16_f32 v56, v28, v29
	v_cvt_pk_bf16_f32 v57, v30, v31
	v_cvt_pk_bf16_f32 v58, v24, v25
	v_cvt_pk_bf16_f32 v59, v26, v27
	s_cbranch_vccnz .LBB0_578
	global_store_dwordx4 v[64:65], v[56:59], off
